# v051 + GLU epilogue: the 16 serialized Z-row loads (load, vmcnt(0), multiply, store per row) become a rolling prefetch with 10 loads in flight and counted waits
# speedup vs baseline: 1.0077x; 1.0077x over previous
; #define GAS __attribute__((address_space(1)))
; __device__ __forceinline__ u32x4 pack8(f32x4 v0, f32x4 v1) { u32x4 w; w.x = cvt_pk_bf16(v0[0], v0[1]); w.y = cvt_pk_bf16(v0[2], v0[3]); w.z = cvt_pk_bf16(v1[0], v1[1]); w.w = cvt_pk_bf16(v1[2], v1[3]); return w; }
; __device__ __forceinline__ void unpack8(u32x4 w, f32x4& v0, f32x4& v1) { v0 = (f32x4){bflo(w.x), bfhi(w.x), bflo(w.y), bfhi(w.y)}; v1 = (f32x4){bflo(w.z), bfhi(w.z), bflo(w.w), bfhi(w.w)}; }
; #define GAS __attribute__((address_space(1)))
;     __device__ __forceinline__ void operator()(const f32x4 (&acc)[2][2][4][2], const Unit& u, int wr, int wc, int fr, int fq) const {
;         const int row0 = u.pm * BM + wr * 64 + fr, col0 = u.pn * BM + wc * 32 + 8 * fq;
;         f32x4 bv[2][2];
; #pragma unroll
;         for (int bj = 0; bj < 2; ++bj)
; #pragma unroll
;             for (int n = 0; n < 2; ++n) bv[bj][n] = *(const f32x4*)(bglu + col0 + bj * HALF + 4 * n);
;         const bf16_t* const zb = Z + (size_t)row0 * 1024 + col0; bf16_t* const sob = SO + (size_t)row0 * 1024 + col0;
; #pragma unroll
;         for (int ai = 0; ai < 2; ++ai)
; #pragma unroll
;             for (int m = 0; m < 4; ++m) { const size_t off = (size_t)(ai * HALF + m * 16) * 1024;
; #pragma unroll
;                 for (int bj = 0; bj < 2; ++bj) { f32x4 z0, z1; unpack8(*(const GAS u32x4*)(zb + off + bj * HALF), z0, z1);
;                     const f32x4 v0 = z0 * sigmoid4(acc[ai][bj][m][0] + bv[bj][0]), v1 = z1 * sigmoid4(acc[ai][bj][m][1] + bv[bj][1]);
;                     *(GAS u32x4*)(sob + off + bj * HALF) = pack8(v0, v1); } }
.LBB0_939:
	v_lshl_or_b32 v160, s24, 8, v164
	v_ashrrev_i32_e32 v161, 31, v160
	v_lshl_add_u64 v[22:23], v[160:161], 2, s[8:9]
	global_load_dwordx4 v[34:37], v[22:23], off offset:16
	global_load_dwordx4 v[38:41], v[22:23], off
	global_load_dwordx4 v[14:17], v[22:23], off offset:528
	s_nop 0
	global_load_dwordx4 v[22:25], v[22:23], off offset:512
	v_lshl_add_u32 v162, s42, 8, v1
	v_ashrrev_i32_e32 v163, 31, v162
	v_lshlrev_b64 v[166:167], 11, v[162:163]
	v_lshl_add_u64 v[162:163], s[4:5], 0, v[166:167]
	v_lshlrev_b64 v[160:161], 1, v[160:161]
	v_lshl_add_u64 v[162:163], v[162:163], 0, v[160:161]
	global_load_dwordx4 v[184:187], v[162:163], off
	global_load_dwordx4 v[188:191], v[162:163], off offset:256
	v_add_co_u32_e32 v242, vcc, s94, v162
	v_addc_co_u32_e32 v243, vcc, 0, v163, vcc
	global_load_dwordx4 v[192:195], v[242:243], off
	global_load_dwordx4 v[196:199], v[242:243], off offset:256
	v_add_co_u32_e32 v242, vcc, s73, v162
	v_addc_co_u32_e32 v243, vcc, 0, v163, vcc
	global_load_dwordx4 v[200:203], v[242:243], off
	global_load_dwordx4 v[222:225], v[242:243], off offset:256
	v_add_co_u32_e32 v242, vcc, s93, v162
	v_addc_co_u32_e32 v243, vcc, 0, v163, vcc
	global_load_dwordx4 v[226:229], v[242:243], off
	global_load_dwordx4 v[230:233], v[242:243], off offset:256
	v_add_co_u32_e32 v242, vcc, s49, v162
	v_addc_co_u32_e32 v243, vcc, 0, v163, vcc
	global_load_dwordx4 v[234:237], v[242:243], off
	global_load_dwordx4 v[238:241], v[242:243], off offset:256
	v_lshl_add_u64 v[166:167], s[10:11], 0, v[166:167]
	v_lshl_add_u64 v[160:161], v[166:167], 0, v[160:161]
	v_readlane_b32 s90, v254, 50
	s_mov_b64 s[42:43], -1
	v_readlane_b32 s91, v254, 51
	s_waitcnt vmcnt(9)
	v_mov_b32_e32 v180, v184
	v_mov_b32_e32 v181, v185
	v_mov_b32_e32 v182, v186
	v_mov_b32_e32 v183, v187
	v_add_co_u32_e32 v242, vcc, s50, v162
	v_addc_co_u32_e32 v243, vcc, 0, v163, vcc
	global_load_dwordx4 v[184:187], v[242:243], off
	v_pk_add_f32 v[142:143], v[142:143], v[36:37]
	v_pk_add_f32 v[146:147], v[146:147], v[40:41]
	v_pk_add_f32 v[144:145], v[144:145], v[38:39]
	v_pk_add_f32 v[140:141], v[140:141], v[34:35]
	v_pk_mul_f32 v[144:145], v[144:145], s[74:75] op_sel_hi:[1,0]
	v_pk_mul_f32 v[146:147], v[146:147], s[74:75] op_sel_hi:[1,0]
	v_pk_mul_f32 v[140:141], v[140:141], s[74:75] op_sel_hi:[1,0]
	v_pk_mul_f32 v[142:143], v[142:143], s[74:75] op_sel_hi:[1,0]
	v_exp_f32_e32 v144, v144
	v_exp_f32_e32 v145, v145
	v_exp_f32_e32 v146, v146
	v_exp_f32_e32 v147, v147
	v_exp_f32_e32 v140, v140
	v_exp_f32_e32 v141, v141
	v_exp_f32_e32 v142, v142
	v_exp_f32_e32 v143, v143
	v_pk_add_f32 v[144:145], v[144:145], 1.0 op_sel_hi:[1,0]
	v_pk_add_f32 v[146:147], v[146:147], 1.0 op_sel_hi:[1,0]
	v_pk_add_f32 v[140:141], v[140:141], 1.0 op_sel_hi:[1,0]
	v_pk_add_f32 v[142:143], v[142:143], 1.0 op_sel_hi:[1,0]
	v_rcp_f32_e32 v144, v144
	v_rcp_f32_e32 v145, v145
	v_rcp_f32_e32 v146, v146
	v_rcp_f32_e32 v147, v147
	v_rcp_f32_e32 v140, v140
	v_rcp_f32_e32 v141, v141
	v_rcp_f32_e32 v142, v142
	v_rcp_f32_e32 v143, v143
	v_lshlrev_b32_e32 v166, 16, v180
	v_and_b32_e32 v167, 0xffff0000, v180
	v_lshlrev_b32_e32 v168, 16, v181
	v_and_b32_e32 v169, 0xffff0000, v181
	v_lshlrev_b32_e32 v172, 16, v182
	v_and_b32_e32 v173, 0xffff0000, v182
	v_lshlrev_b32_e32 v180, 16, v183
	v_and_b32_e32 v181, 0xffff0000, v183
	v_pk_mul_f32 v[146:147], v[146:147], v[168:169]
	v_pk_mul_f32 v[144:145], v[144:145], v[166:167]
	v_pk_mul_f32 v[166:167], v[142:143], v[180:181]
	v_pk_mul_f32 v[142:143], v[140:141], v[172:173]
	v_cvt_pk_bf16_f32 v140, v144, v145
	v_cvt_pk_bf16_f32 v141, v146, v147
	v_cvt_pk_bf16_f32 v142, v142, v143
	v_cvt_pk_bf16_f32 v143, v166, v167
	global_store_dwordx4 v[160:161], v[140:143], off
	v_pk_add_f32 v[138:139], v[138:139], v[24:25]
	v_pk_add_f32 v[136:137], v[136:137], v[22:23]
	v_pk_add_f32 v[134:135], v[134:135], v[16:17]
	v_pk_add_f32 v[132:133], v[132:133], v[14:15]
	v_pk_mul_f32 v[136:137], v[136:137], s[74:75] op_sel_hi:[1,0]
	v_pk_mul_f32 v[138:139], v[138:139], s[74:75] op_sel_hi:[1,0]
	v_pk_mul_f32 v[132:133], v[132:133], s[74:75] op_sel_hi:[1,0]
	v_pk_mul_f32 v[134:135], v[134:135], s[74:75] op_sel_hi:[1,0]
	v_exp_f32_e32 v136, v136
	v_exp_f32_e32 v137, v137
	v_exp_f32_e32 v138, v138
	v_exp_f32_e32 v139, v139
	v_exp_f32_e32 v132, v132
	v_exp_f32_e32 v133, v133
	v_exp_f32_e32 v134, v134
	v_exp_f32_e32 v135, v135
	v_pk_add_f32 v[136:137], v[136:137], 1.0 op_sel_hi:[1,0]
	v_pk_add_f32 v[138:139], v[138:139], 1.0 op_sel_hi:[1,0]
	v_pk_add_f32 v[132:133], v[132:133], 1.0 op_sel_hi:[1,0]
	v_pk_add_f32 v[134:135], v[134:135], 1.0 op_sel_hi:[1,0]
	v_rcp_f32_e32 v136, v136
	v_rcp_f32_e32 v137, v137
	v_rcp_f32_e32 v138, v138
	v_rcp_f32_e32 v139, v139
	v_rcp_f32_e32 v132, v132
	v_rcp_f32_e32 v133, v133
	v_rcp_f32_e32 v134, v134
	v_rcp_f32_e32 v135, v135
	v_pk_add_f32 v[128:129], v[128:129], v[38:39]
	v_pk_add_f32 v[124:125], v[124:125], v[34:35]
	v_pk_add_f32 v[130:131], v[130:131], v[40:41]
	v_pk_mul_f32 v[128:129], v[128:129], s[74:75] op_sel_hi:[1,0]
	v_pk_add_f32 v[126:127], v[126:127], v[36:37]
	v_pk_mul_f32 v[124:125], v[124:125], s[74:75] op_sel_hi:[1,0]
	v_pk_mul_f32 v[130:131], v[130:131], s[74:75] op_sel_hi:[1,0]
	v_exp_f32_e32 v128, v128
	v_exp_f32_e32 v129, v129
	v_pk_mul_f32 v[126:127], v[126:127], s[74:75] op_sel_hi:[1,0]
	v_exp_f32_e32 v124, v124
	v_exp_f32_e32 v125, v125
	v_exp_f32_e32 v130, v130
	v_exp_f32_e32 v131, v131
	v_exp_f32_e32 v126, v126
	v_exp_f32_e32 v127, v127
	v_pk_add_f32 v[128:129], v[128:129], 1.0 op_sel_hi:[1,0]
	v_pk_add_f32 v[124:125], v[124:125], 1.0 op_sel_hi:[1,0]
	v_pk_add_f32 v[130:131], v[130:131], 1.0 op_sel_hi:[1,0]
	v_rcp_f32_e32 v128, v128
	v_rcp_f32_e32 v129, v129
	v_pk_add_f32 v[126:127], v[126:127], 1.0 op_sel_hi:[1,0]
	v_rcp_f32_e32 v124, v124
	v_rcp_f32_e32 v125, v125
	v_rcp_f32_e32 v130, v130
	v_rcp_f32_e32 v131, v131
	v_rcp_f32_e32 v126, v126
	v_rcp_f32_e32 v127, v127
	v_pk_add_f32 v[122:123], v[122:123], v[24:25]
	v_pk_add_f32 v[120:121], v[120:121], v[22:23]
	v_pk_add_f32 v[118:119], v[118:119], v[16:17]
	v_pk_add_f32 v[116:117], v[116:117], v[14:15]
	v_pk_mul_f32 v[120:121], v[120:121], s[74:75] op_sel_hi:[1,0]
	v_pk_mul_f32 v[122:123], v[122:123], s[74:75] op_sel_hi:[1,0]
	v_pk_mul_f32 v[116:117], v[116:117], s[74:75] op_sel_hi:[1,0]
	v_pk_mul_f32 v[118:119], v[118:119], s[74:75] op_sel_hi:[1,0]
	v_exp_f32_e32 v120, v120
	v_exp_f32_e32 v121, v121
	v_exp_f32_e32 v122, v122
	v_exp_f32_e32 v123, v123
	v_exp_f32_e32 v116, v116
	v_exp_f32_e32 v117, v117
	v_exp_f32_e32 v118, v118
	v_exp_f32_e32 v119, v119
	v_pk_add_f32 v[120:121], v[120:121], 1.0 op_sel_hi:[1,0]
	v_pk_add_f32 v[122:123], v[122:123], 1.0 op_sel_hi:[1,0]
	v_pk_add_f32 v[116:117], v[116:117], 1.0 op_sel_hi:[1,0]
	v_pk_add_f32 v[118:119], v[118:119], 1.0 op_sel_hi:[1,0]
	v_rcp_f32_e32 v120, v120
	v_rcp_f32_e32 v121, v121
	v_rcp_f32_e32 v122, v122
	s_waitcnt vmcnt(10)
; #define GAS __attribute__((address_space(1)))
; __device__ __forceinline__ u32x4 pack8(f32x4 v0, f32x4 v1) { u32x4 w; w.x = cvt_pk_bf16(v0[0], v0[1]); w.y = cvt_pk_bf16(v0[2], v0[3]); w.z = cvt_pk_bf16(v1[0], v1[1]); w.w = cvt_pk_bf16(v1[2], v1[3]); return w; }
; __device__ __forceinline__ void unpack8(u32x4 w, f32x4& v0, f32x4& v1) { v0 = (f32x4){bflo(w.x), bfhi(w.x), bflo(w.y), bfhi(w.y)}; v1 = (f32x4){bflo(w.z), bfhi(w.z), bflo(w.w), bfhi(w.w)}; }
; #define GAS __attribute__((address_space(1)))
;     __device__ __forceinline__ void operator()(const f32x4 (&acc)[2][2][4][2], const Unit& u, int wr, int wc, int fr, int fq) const {
;     ...
; #pragma unroll
;         for (int ai = 0; ai < 2; ++ai)
; #pragma unroll
;             for (int m = 0; m < 4; ++m) { const size_t off = (size_t)(ai * HALF + m * 16) * 1024;
; #pragma unroll
;                 for (int bj = 0; bj < 2; ++bj) { f32x4 z0, z1; unpack8(*(const GAS u32x4*)(zb + off + bj * HALF), z0, z1);
;                     const f32x4 v0 = z0 * sigmoid4(acc[ai][bj][m][0] + bv[bj][0]), v1 = z1 * sigmoid4(acc[ai][bj][m][1] + bv[bj][1]);
;                     *(GAS u32x4*)(sob + off + bj * HALF) = pack8(v0, v1); } }
	v_mov_b32_e32 v140, v188
	v_mov_b32_e32 v141, v189
	v_mov_b32_e32 v142, v190
	v_mov_b32_e32 v143, v191
	global_load_dwordx4 v[188:191], v[242:243], off offset:256
	v_lshlrev_b32_e32 v144, 16, v140
	v_and_b32_e32 v145, 0xffff0000, v140
	v_lshlrev_b32_e32 v140, 16, v141
	v_and_b32_e32 v141, 0xffff0000, v141
	v_lshlrev_b32_e32 v146, 16, v142
	v_and_b32_e32 v147, 0xffff0000, v142
	v_lshlrev_b32_e32 v142, 16, v143
	v_and_b32_e32 v143, 0xffff0000, v143
	v_pk_mul_f32 v[138:139], v[138:139], v[140:141]
	v_pk_mul_f32 v[136:137], v[136:137], v[144:145]
	v_pk_mul_f32 v[140:141], v[134:135], v[142:143]
	v_pk_mul_f32 v[134:135], v[132:133], v[146:147]
	v_cvt_pk_bf16_f32 v132, v136, v137
	v_cvt_pk_bf16_f32 v133, v138, v139
	v_cvt_pk_bf16_f32 v134, v134, v135
	v_cvt_pk_bf16_f32 v135, v140, v141
	global_store_dwordx4 v[160:161], v[132:135], off offset:256
	v_rcp_f32_e32 v123, v123
	v_rcp_f32_e32 v116, v116
	v_add_co_u32_e32 v132, vcc, s94, v162
	v_rcp_f32_e32 v117, v117
	s_nop 0
	v_addc_co_u32_e32 v133, vcc, 0, v163, vcc
	v_rcp_f32_e32 v118, v118
	v_rcp_f32_e32 v119, v119
	v_pk_add_f32 v[112:113], v[112:113], v[38:39]
	v_pk_add_f32 v[108:109], v[108:109], v[34:35]
	v_pk_add_f32 v[114:115], v[114:115], v[40:41]
	v_pk_mul_f32 v[112:113], v[112:113], s[74:75] op_sel_hi:[1,0]
	v_pk_add_f32 v[110:111], v[110:111], v[36:37]
	v_pk_mul_f32 v[108:109], v[108:109], s[74:75] op_sel_hi:[1,0]
	v_pk_mul_f32 v[114:115], v[114:115], s[74:75] op_sel_hi:[1,0]
	v_exp_f32_e32 v112, v112
	v_exp_f32_e32 v113, v113
	v_pk_mul_f32 v[110:111], v[110:111], s[74:75] op_sel_hi:[1,0]
	v_exp_f32_e32 v108, v108
	v_exp_f32_e32 v109, v109
	v_exp_f32_e32 v114, v114
	v_exp_f32_e32 v115, v115
	v_exp_f32_e32 v110, v110
	v_exp_f32_e32 v111, v111
	v_pk_add_f32 v[112:113], v[112:113], 1.0 op_sel_hi:[1,0]
	v_pk_add_f32 v[108:109], v[108:109], 1.0 op_sel_hi:[1,0]
	v_pk_add_f32 v[114:115], v[114:115], 1.0 op_sel_hi:[1,0]
	v_rcp_f32_e32 v112, v112
	v_rcp_f32_e32 v113, v113
	v_pk_add_f32 v[110:111], v[110:111], 1.0 op_sel_hi:[1,0]
	v_rcp_f32_e32 v108, v108
	v_rcp_f32_e32 v109, v109
	v_rcp_f32_e32 v114, v114
	v_rcp_f32_e32 v115, v115
	v_rcp_f32_e32 v110, v110
	v_rcp_f32_e32 v111, v111
	v_pk_add_f32 v[106:107], v[106:107], v[24:25]
	v_pk_add_f32 v[104:105], v[104:105], v[22:23]
	v_pk_add_f32 v[102:103], v[102:103], v[16:17]
	v_pk_add_f32 v[100:101], v[100:101], v[14:15]
	v_pk_mul_f32 v[104:105], v[104:105], s[74:75] op_sel_hi:[1,0]
	v_pk_mul_f32 v[106:107], v[106:107], s[74:75] op_sel_hi:[1,0]
	v_pk_mul_f32 v[100:101], v[100:101], s[74:75] op_sel_hi:[1,0]
	v_pk_mul_f32 v[102:103], v[102:103], s[74:75] op_sel_hi:[1,0]
	v_exp_f32_e32 v104, v104
	v_exp_f32_e32 v105, v105
	v_exp_f32_e32 v106, v106
	v_exp_f32_e32 v107, v107
	v_exp_f32_e32 v100, v100
	v_exp_f32_e32 v101, v101
	v_exp_f32_e32 v102, v102
	v_exp_f32_e32 v103, v103
	v_pk_add_f32 v[104:105], v[104:105], 1.0 op_sel_hi:[1,0]
	v_pk_add_f32 v[106:107], v[106:107], 1.0 op_sel_hi:[1,0]
	v_pk_add_f32 v[100:101], v[100:101], 1.0 op_sel_hi:[1,0]
	v_pk_add_f32 v[102:103], v[102:103], 1.0 op_sel_hi:[1,0]
	v_rcp_f32_e32 v104, v104
	v_rcp_f32_e32 v105, v105
	v_rcp_f32_e32 v106, v106
	v_rcp_f32_e32 v107, v107
	v_rcp_f32_e32 v100, v100
	v_rcp_f32_e32 v101, v101
	v_rcp_f32_e32 v102, v102
	v_rcp_f32_e32 v103, v103
	v_pk_add_f32 v[94:95], v[94:95], v[38:39]
	v_pk_add_f32 v[90:91], v[90:91], v[34:35]
	v_pk_add_f32 v[96:97], v[96:97], v[40:41]
	v_pk_mul_f32 v[94:95], v[94:95], s[74:75] op_sel_hi:[1,0]
	v_pk_add_f32 v[92:93], v[92:93], v[36:37]
	v_pk_mul_f32 v[90:91], v[90:91], s[74:75] op_sel_hi:[1,0]
	v_pk_mul_f32 v[96:97], v[96:97], s[74:75] op_sel_hi:[1,0]
	v_exp_f32_e32 v94, v94
	v_exp_f32_e32 v95, v95
	v_pk_mul_f32 v[92:93], v[92:93], s[74:75] op_sel_hi:[1,0]
	v_exp_f32_e32 v90, v90
	v_exp_f32_e32 v91, v91
	v_exp_f32_e32 v96, v96
	v_exp_f32_e32 v97, v97
	v_exp_f32_e32 v92, v92
	v_exp_f32_e32 v93, v93
	v_pk_add_f32 v[94:95], v[94:95], 1.0 op_sel_hi:[1,0]
	v_pk_add_f32 v[90:91], v[90:91], 1.0 op_sel_hi:[1,0]
	v_pk_add_f32 v[96:97], v[96:97], 1.0 op_sel_hi:[1,0]
	v_rcp_f32_e32 v94, v94
	v_rcp_f32_e32 v95, v95
	s_waitcnt vmcnt(11)
	v_mov_b32_e32 v134, v192
	v_mov_b32_e32 v135, v193
	v_mov_b32_e32 v136, v194
	v_mov_b32_e32 v137, v195
	v_add_co_u32_e32 v242, vcc, s51, v162
	v_addc_co_u32_e32 v243, vcc, 0, v163, vcc
	global_load_dwordx4 v[192:195], v[242:243], off
	v_lshlrev_b32_e32 v138, 16, v134
	v_and_b32_e32 v139, 0xffff0000, v134
	v_lshlrev_b32_e32 v140, 16, v136
	v_and_b32_e32 v141, 0xffff0000, v136
	v_lshlrev_b32_e32 v134, 16, v135
	v_and_b32_e32 v135, 0xffff0000, v135
	v_lshlrev_b32_e32 v136, 16, v137
	v_and_b32_e32 v137, 0xffff0000, v137
	v_pk_mul_f32 v[128:129], v[128:129], v[138:139]
	v_pk_mul_f32 v[124:125], v[124:125], v[140:141]
	v_pk_mul_f32 v[130:131], v[130:131], v[134:135]
	v_pk_mul_f32 v[134:135], v[126:127], v[136:137]
	v_cvt_pk_bf16_f32 v126, v128, v129
	v_cvt_pk_bf16_f32 v128, v124, v125
	v_add_co_u32_e32 v124, vcc, s94, v160
	v_cvt_pk_bf16_f32 v127, v130, v131
	v_cvt_pk_bf16_f32 v129, v134, v135
	v_addc_co_u32_e32 v125, vcc, 0, v161, vcc
	global_store_dwordx4 v[124:125], v[126:129], off
	v_pk_add_f32 v[92:93], v[92:93], 1.0 op_sel_hi:[1,0]
	v_rcp_f32_e32 v90, v90
	v_rcp_f32_e32 v91, v91
	v_rcp_f32_e32 v96, v96
	v_rcp_f32_e32 v97, v97
	v_rcp_f32_e32 v92, v92
	v_rcp_f32_e32 v93, v93
	v_pk_add_f32 v[88:89], v[88:89], v[24:25]
	v_pk_add_f32 v[86:87], v[86:87], v[22:23]
	v_pk_add_f32 v[84:85], v[84:85], v[16:17]
	v_pk_add_f32 v[82:83], v[82:83], v[14:15]
	v_pk_mul_f32 v[86:87], v[86:87], s[74:75] op_sel_hi:[1,0]
	v_pk_mul_f32 v[88:89], v[88:89], s[74:75] op_sel_hi:[1,0]
	v_pk_mul_f32 v[82:83], v[82:83], s[74:75] op_sel_hi:[1,0]
; #define GAS __attribute__((address_space(1)))
; __device__ __forceinline__ u32x4 pack8(f32x4 v0, f32x4 v1) { u32x4 w; w.x = cvt_pk_bf16(v0[0], v0[1]); w.y = cvt_pk_bf16(v0[2], v0[3]); w.z = cvt_pk_bf16(v1[0], v1[1]); w.w = cvt_pk_bf16(v1[2], v1[3]); return w; }
; __device__ __forceinline__ void unpack8(u32x4 w, f32x4& v0, f32x4& v1) { v0 = (f32x4){bflo(w.x), bfhi(w.x), bflo(w.y), bfhi(w.y)}; v1 = (f32x4){bflo(w.z), bfhi(w.z), bflo(w.w), bfhi(w.w)}; }
; #define GAS __attribute__((address_space(1)))
;     __device__ __forceinline__ void operator()(const f32x4 (&acc)[2][2][4][2], const Unit& u, int wr, int wc, int fr, int fq) const {
;     ...
; #pragma unroll
;         for (int ai = 0; ai < 2; ++ai)
; #pragma unroll
;             for (int m = 0; m < 4; ++m) { const size_t off = (size_t)(ai * HALF + m * 16) * 1024;
; #pragma unroll
;                 for (int bj = 0; bj < 2; ++bj) { f32x4 z0, z1; unpack8(*(const GAS u32x4*)(zb + off + bj * HALF), z0, z1);
;                     const f32x4 v0 = z0 * sigmoid4(acc[ai][bj][m][0] + bv[bj][0]), v1 = z1 * sigmoid4(acc[ai][bj][m][1] + bv[bj][1]);
;                     *(GAS u32x4*)(sob + off + bj * HALF) = pack8(v0, v1); } }
	v_pk_mul_f32 v[84:85], v[84:85], s[74:75] op_sel_hi:[1,0]
	v_exp_f32_e32 v86, v86
	v_exp_f32_e32 v87, v87
	v_exp_f32_e32 v88, v88
	v_exp_f32_e32 v89, v89
	v_exp_f32_e32 v82, v82
	v_exp_f32_e32 v83, v83
	v_exp_f32_e32 v84, v84
	v_exp_f32_e32 v85, v85
	v_pk_add_f32 v[86:87], v[86:87], 1.0 op_sel_hi:[1,0]
	v_pk_add_f32 v[88:89], v[88:89], 1.0 op_sel_hi:[1,0]
	v_pk_add_f32 v[82:83], v[82:83], 1.0 op_sel_hi:[1,0]
	v_pk_add_f32 v[84:85], v[84:85], 1.0 op_sel_hi:[1,0]
	v_rcp_f32_e32 v86, v86
	v_rcp_f32_e32 v87, v87
	v_rcp_f32_e32 v88, v88
	v_rcp_f32_e32 v89, v89
	v_rcp_f32_e32 v82, v82
	v_rcp_f32_e32 v83, v83
	v_rcp_f32_e32 v84, v84
	v_rcp_f32_e32 v85, v85
	v_pk_add_f32 v[78:79], v[78:79], v[38:39]
	v_pk_add_f32 v[74:75], v[74:75], v[34:35]
	v_pk_add_f32 v[80:81], v[80:81], v[40:41]
	v_pk_mul_f32 v[78:79], v[78:79], s[74:75] op_sel_hi:[1,0]
	v_pk_add_f32 v[76:77], v[76:77], v[36:37]
	v_pk_mul_f32 v[74:75], v[74:75], s[74:75] op_sel_hi:[1,0]
	v_pk_mul_f32 v[80:81], v[80:81], s[74:75] op_sel_hi:[1,0]
	v_exp_f32_e32 v78, v78
	v_exp_f32_e32 v79, v79
	v_pk_mul_f32 v[76:77], v[76:77], s[74:75] op_sel_hi:[1,0]
	v_exp_f32_e32 v74, v74
	v_exp_f32_e32 v75, v75
	v_exp_f32_e32 v80, v80
	v_exp_f32_e32 v81, v81
	v_exp_f32_e32 v76, v76
	v_exp_f32_e32 v77, v77
	v_pk_add_f32 v[78:79], v[78:79], 1.0 op_sel_hi:[1,0]
	v_pk_add_f32 v[74:75], v[74:75], 1.0 op_sel_hi:[1,0]
	v_pk_add_f32 v[80:81], v[80:81], 1.0 op_sel_hi:[1,0]
	v_rcp_f32_e32 v78, v78
	v_rcp_f32_e32 v79, v79
	v_pk_add_f32 v[76:77], v[76:77], 1.0 op_sel_hi:[1,0]
	v_rcp_f32_e32 v74, v74
	v_rcp_f32_e32 v75, v75
	v_rcp_f32_e32 v80, v80
	v_rcp_f32_e32 v81, v81
	v_rcp_f32_e32 v76, v76
	v_rcp_f32_e32 v77, v77
	v_pk_add_f32 v[72:73], v[72:73], v[24:25]
	v_pk_add_f32 v[70:71], v[70:71], v[22:23]
	v_pk_add_f32 v[68:69], v[68:69], v[16:17]
	v_pk_add_f32 v[66:67], v[66:67], v[14:15]
	v_pk_mul_f32 v[70:71], v[70:71], s[74:75] op_sel_hi:[1,0]
	v_pk_mul_f32 v[72:73], v[72:73], s[74:75] op_sel_hi:[1,0]
	v_pk_mul_f32 v[66:67], v[66:67], s[74:75] op_sel_hi:[1,0]
	v_pk_mul_f32 v[68:69], v[68:69], s[74:75] op_sel_hi:[1,0]
	v_exp_f32_e32 v70, v70
	v_exp_f32_e32 v71, v71
	v_exp_f32_e32 v72, v72
	v_exp_f32_e32 v73, v73
	v_exp_f32_e32 v66, v66
	v_exp_f32_e32 v67, v67
	v_exp_f32_e32 v68, v68
	v_exp_f32_e32 v69, v69
	s_waitcnt vmcnt(12)
	v_mov_b32_e32 v126, v196
	v_mov_b32_e32 v127, v197
	v_mov_b32_e32 v128, v198
	v_mov_b32_e32 v129, v199
	global_load_dwordx4 v[196:199], v[242:243], off offset:256
	v_lshlrev_b32_e32 v130, 16, v126
	v_and_b32_e32 v131, 0xffff0000, v126
	v_lshlrev_b32_e32 v126, 16, v127
	v_and_b32_e32 v127, 0xffff0000, v127
	v_lshlrev_b32_e32 v132, 16, v128
	v_and_b32_e32 v133, 0xffff0000, v128
	v_lshlrev_b32_e32 v128, 16, v129
	v_and_b32_e32 v129, 0xffff0000, v129
	v_pk_mul_f32 v[122:123], v[122:123], v[126:127]
	v_pk_mul_f32 v[120:121], v[120:121], v[130:131]
	v_pk_mul_f32 v[126:127], v[118:119], v[128:129]
	v_pk_mul_f32 v[118:119], v[116:117], v[132:133]
	v_cvt_pk_bf16_f32 v116, v120, v121
	v_cvt_pk_bf16_f32 v117, v122, v123
	v_cvt_pk_bf16_f32 v118, v118, v119
	v_cvt_pk_bf16_f32 v119, v126, v127
	global_store_dwordx4 v[124:125], v[116:119], off offset:256
	v_pk_add_f32 v[70:71], v[70:71], 1.0 op_sel_hi:[1,0]
	v_pk_add_f32 v[72:73], v[72:73], 1.0 op_sel_hi:[1,0]
	v_add_co_u32_e32 v116, vcc, s73, v162
	v_pk_add_f32 v[66:67], v[66:67], 1.0 op_sel_hi:[1,0]
	s_nop 0
	v_addc_co_u32_e32 v117, vcc, 0, v163, vcc
	v_pk_add_f32 v[68:69], v[68:69], 1.0 op_sel_hi:[1,0]
	v_rcp_f32_e32 v70, v70
	v_rcp_f32_e32 v71, v71
	v_rcp_f32_e32 v72, v72
	v_rcp_f32_e32 v73, v73
	v_rcp_f32_e32 v66, v66
	v_rcp_f32_e32 v67, v67
	v_rcp_f32_e32 v68, v68
	v_rcp_f32_e32 v69, v69
	v_pk_add_f32 v[62:63], v[62:63], v[38:39]
	v_pk_add_f32 v[58:59], v[58:59], v[34:35]
	v_pk_add_f32 v[64:65], v[64:65], v[40:41]
	v_pk_mul_f32 v[62:63], v[62:63], s[74:75] op_sel_hi:[1,0]
	v_pk_add_f32 v[60:61], v[60:61], v[36:37]
	v_pk_mul_f32 v[58:59], v[58:59], s[74:75] op_sel_hi:[1,0]
	v_pk_mul_f32 v[64:65], v[64:65], s[74:75] op_sel_hi:[1,0]
	v_exp_f32_e32 v62, v62
	v_exp_f32_e32 v63, v63
	v_pk_mul_f32 v[60:61], v[60:61], s[74:75] op_sel_hi:[1,0]
	v_exp_f32_e32 v58, v58
	v_exp_f32_e32 v59, v59
	v_exp_f32_e32 v64, v64
	v_exp_f32_e32 v65, v65
	v_exp_f32_e32 v60, v60
	v_exp_f32_e32 v61, v61
	v_pk_add_f32 v[62:63], v[62:63], 1.0 op_sel_hi:[1,0]
	v_pk_add_f32 v[58:59], v[58:59], 1.0 op_sel_hi:[1,0]
	v_pk_add_f32 v[64:65], v[64:65], 1.0 op_sel_hi:[1,0]
	v_rcp_f32_e32 v62, v62
	v_rcp_f32_e32 v63, v63
	v_pk_add_f32 v[60:61], v[60:61], 1.0 op_sel_hi:[1,0]
	v_rcp_f32_e32 v58, v58
	v_rcp_f32_e32 v59, v59
	v_rcp_f32_e32 v64, v64
	v_rcp_f32_e32 v65, v65
	v_rcp_f32_e32 v60, v60
	v_rcp_f32_e32 v61, v61
	v_pk_add_f32 v[56:57], v[56:57], v[24:25]
	v_pk_add_f32 v[54:55], v[54:55], v[22:23]
	v_pk_add_f32 v[52:53], v[52:53], v[16:17]
	v_pk_add_f32 v[50:51], v[50:51], v[14:15]
	v_pk_mul_f32 v[54:55], v[54:55], s[74:75] op_sel_hi:[1,0]
	v_pk_mul_f32 v[56:57], v[56:57], s[74:75] op_sel_hi:[1,0]
	v_pk_mul_f32 v[50:51], v[50:51], s[74:75] op_sel_hi:[1,0]
	v_pk_mul_f32 v[52:53], v[52:53], s[74:75] op_sel_hi:[1,0]
	v_exp_f32_e32 v54, v54
	v_exp_f32_e32 v55, v55
	v_exp_f32_e32 v56, v56
	v_exp_f32_e32 v57, v57
	v_exp_f32_e32 v50, v50
	v_exp_f32_e32 v51, v51
	v_exp_f32_e32 v52, v52
	v_exp_f32_e32 v53, v53
	v_pk_add_f32 v[54:55], v[54:55], 1.0 op_sel_hi:[1,0]
	v_pk_add_f32 v[56:57], v[56:57], 1.0 op_sel_hi:[1,0]
	v_pk_add_f32 v[50:51], v[50:51], 1.0 op_sel_hi:[1,0]
	v_pk_add_f32 v[52:53], v[52:53], 1.0 op_sel_hi:[1,0]
	v_rcp_f32_e32 v54, v54
	v_rcp_f32_e32 v55, v55
	v_rcp_f32_e32 v56, v56
	v_rcp_f32_e32 v57, v57
	v_rcp_f32_e32 v50, v50
	v_rcp_f32_e32 v51, v51
	v_rcp_f32_e32 v52, v52
	v_rcp_f32_e32 v53, v53
	v_pk_add_f32 v[46:47], v[46:47], v[38:39]
	v_pk_add_f32 v[42:43], v[42:43], v[34:35]
	v_pk_add_f32 v[48:49], v[48:49], v[40:41]
	v_pk_mul_f32 v[46:47], v[46:47], s[74:75] op_sel_hi:[1,0]
	v_pk_add_f32 v[44:45], v[44:45], v[36:37]
	v_pk_mul_f32 v[42:43], v[42:43], s[74:75] op_sel_hi:[1,0]
	v_pk_mul_f32 v[48:49], v[48:49], s[74:75] op_sel_hi:[1,0]
	v_exp_f32_e32 v46, v46
	v_exp_f32_e32 v47, v47
	v_pk_mul_f32 v[44:45], v[44:45], s[74:75] op_sel_hi:[1,0]
	v_exp_f32_e32 v42, v42
	v_exp_f32_e32 v43, v43
	v_exp_f32_e32 v48, v48
	v_exp_f32_e32 v49, v49
	s_waitcnt vmcnt(13)
; #define GAS __attribute__((address_space(1)))
; __device__ __forceinline__ u32x4 pack8(f32x4 v0, f32x4 v1) { u32x4 w; w.x = cvt_pk_bf16(v0[0], v0[1]); w.y = cvt_pk_bf16(v0[2], v0[3]); w.z = cvt_pk_bf16(v1[0], v1[1]); w.w = cvt_pk_bf16(v1[2], v1[3]); return w; }
; __device__ __forceinline__ void unpack8(u32x4 w, f32x4& v0, f32x4& v1) { v0 = (f32x4){bflo(w.x), bfhi(w.x), bflo(w.y), bfhi(w.y)}; v1 = (f32x4){bflo(w.z), bfhi(w.z), bflo(w.w), bfhi(w.w)}; }
; #define GAS __attribute__((address_space(1)))
;     __device__ __forceinline__ void operator()(const f32x4 (&acc)[2][2][4][2], const Unit& u, int wr, int wc, int fr, int fq) const {
;     ...
; #pragma unroll
;         for (int ai = 0; ai < 2; ++ai)
; #pragma unroll
;             for (int m = 0; m < 4; ++m) { const size_t off = (size_t)(ai * HALF + m * 16) * 1024;
; #pragma unroll
;                 for (int bj = 0; bj < 2; ++bj) { f32x4 z0, z1; unpack8(*(const GAS u32x4*)(zb + off + bj * HALF), z0, z1);
;                     const f32x4 v0 = z0 * sigmoid4(acc[ai][bj][m][0] + bv[bj][0]), v1 = z1 * sigmoid4(acc[ai][bj][m][1] + bv[bj][1]);
;                     *(GAS u32x4*)(sob + off + bj * HALF) = pack8(v0, v1); } }
	v_mov_b32_e32 v118, v200
	v_mov_b32_e32 v119, v201
	v_mov_b32_e32 v120, v202
	v_mov_b32_e32 v121, v203
	v_add_co_u32_e32 v242, vcc, s66, v162
	v_addc_co_u32_e32 v243, vcc, 0, v163, vcc
	global_load_dwordx4 v[200:203], v[242:243], off
	v_lshlrev_b32_e32 v122, 16, v118
	v_and_b32_e32 v123, 0xffff0000, v118
	v_lshlrev_b32_e32 v124, 16, v120
	v_and_b32_e32 v125, 0xffff0000, v120
	v_lshlrev_b32_e32 v118, 16, v119
	v_and_b32_e32 v119, 0xffff0000, v119
	v_lshlrev_b32_e32 v120, 16, v121
	v_and_b32_e32 v121, 0xffff0000, v121
	v_pk_mul_f32 v[112:113], v[112:113], v[122:123]
	v_pk_mul_f32 v[108:109], v[108:109], v[124:125]
	v_pk_mul_f32 v[114:115], v[114:115], v[118:119]
	v_pk_mul_f32 v[118:119], v[110:111], v[120:121]
	v_cvt_pk_bf16_f32 v110, v112, v113
	v_cvt_pk_bf16_f32 v112, v108, v109
	v_add_co_u32_e32 v108, vcc, s73, v160
	v_cvt_pk_bf16_f32 v111, v114, v115
	v_cvt_pk_bf16_f32 v113, v118, v119
	v_addc_co_u32_e32 v109, vcc, 0, v161, vcc
	global_store_dwordx4 v[108:109], v[110:113], off
	v_exp_f32_e32 v44, v44
	v_exp_f32_e32 v45, v45
	v_pk_add_f32 v[46:47], v[46:47], 1.0 op_sel_hi:[1,0]
	v_pk_add_f32 v[42:43], v[42:43], 1.0 op_sel_hi:[1,0]
	v_pk_add_f32 v[48:49], v[48:49], 1.0 op_sel_hi:[1,0]
	v_rcp_f32_e32 v46, v46
	v_rcp_f32_e32 v47, v47
	v_pk_add_f32 v[44:45], v[44:45], 1.0 op_sel_hi:[1,0]
	v_rcp_f32_e32 v42, v42
	v_rcp_f32_e32 v43, v43
	v_rcp_f32_e32 v48, v48
	v_rcp_f32_e32 v49, v49
	v_rcp_f32_e32 v44, v44
	v_rcp_f32_e32 v45, v45
	v_pk_add_f32 v[32:33], v[32:33], v[24:25]
	v_pk_add_f32 v[30:31], v[30:31], v[22:23]
	v_pk_add_f32 v[28:29], v[28:29], v[16:17]
	v_pk_add_f32 v[26:27], v[26:27], v[14:15]
	v_pk_mul_f32 v[30:31], v[30:31], s[74:75] op_sel_hi:[1,0]
	v_pk_mul_f32 v[32:33], v[32:33], s[74:75] op_sel_hi:[1,0]
	v_pk_mul_f32 v[26:27], v[26:27], s[74:75] op_sel_hi:[1,0]
	v_pk_mul_f32 v[28:29], v[28:29], s[74:75] op_sel_hi:[1,0]
	v_exp_f32_e32 v30, v30
	v_exp_f32_e32 v31, v31
	v_exp_f32_e32 v32, v32
	v_exp_f32_e32 v33, v33
	v_exp_f32_e32 v26, v26
	v_exp_f32_e32 v27, v27
	v_exp_f32_e32 v28, v28
	v_exp_f32_e32 v29, v29
	v_pk_add_f32 v[30:31], v[30:31], 1.0 op_sel_hi:[1,0]
	v_pk_add_f32 v[32:33], v[32:33], 1.0 op_sel_hi:[1,0]
	v_pk_add_f32 v[26:27], v[26:27], 1.0 op_sel_hi:[1,0]
	v_pk_add_f32 v[28:29], v[28:29], 1.0 op_sel_hi:[1,0]
	v_rcp_f32_e32 v30, v30
	v_rcp_f32_e32 v31, v31
	v_rcp_f32_e32 v32, v32
	v_rcp_f32_e32 v33, v33
	v_rcp_f32_e32 v26, v26
	v_rcp_f32_e32 v27, v27
	v_rcp_f32_e32 v28, v28
	v_rcp_f32_e32 v29, v29
	v_pk_add_f32 v[18:19], v[18:19], v[38:39]
	v_pk_add_f32 v[20:21], v[20:21], v[40:41]
	v_pk_mul_f32 v[18:19], v[18:19], s[74:75] op_sel_hi:[1,0]
	v_pk_add_f32 v[12:13], v[12:13], v[36:37]
	v_pk_add_f32 v[10:11], v[10:11], v[34:35]
	v_pk_mul_f32 v[20:21], v[20:21], s[74:75] op_sel_hi:[1,0]
	v_exp_f32_e32 v18, v18
	v_exp_f32_e32 v19, v19
	v_pk_mul_f32 v[10:11], v[10:11], s[74:75] op_sel_hi:[1,0]
	v_pk_mul_f32 v[12:13], v[12:13], s[74:75] op_sel_hi:[1,0]
	v_exp_f32_e32 v20, v20
	v_exp_f32_e32 v21, v21
	v_exp_f32_e32 v10, v10
	v_exp_f32_e32 v11, v11
	v_exp_f32_e32 v12, v12
	v_exp_f32_e32 v13, v13
	v_pk_add_f32 v[18:19], v[18:19], 1.0 op_sel_hi:[1,0]
	v_pk_add_f32 v[20:21], v[20:21], 1.0 op_sel_hi:[1,0]
	v_rcp_f32_e32 v18, v18
	v_rcp_f32_e32 v19, v19
	v_pk_add_f32 v[10:11], v[10:11], 1.0 op_sel_hi:[1,0]
	v_pk_add_f32 v[12:13], v[12:13], 1.0 op_sel_hi:[1,0]
	v_rcp_f32_e32 v20, v20
	v_rcp_f32_e32 v21, v21
	v_rcp_f32_e32 v10, v10
	v_rcp_f32_e32 v11, v11
	v_rcp_f32_e32 v12, v12
	v_rcp_f32_e32 v13, v13
	v_pk_add_f32 v[8:9], v[8:9], v[24:25]
	v_pk_add_f32 v[6:7], v[6:7], v[22:23]
	v_pk_add_f32 v[4:5], v[4:5], v[16:17]
	v_pk_add_f32 v[2:3], v[2:3], v[14:15]
	v_pk_mul_f32 v[6:7], v[6:7], s[74:75] op_sel_hi:[1,0]
	v_pk_mul_f32 v[8:9], v[8:9], s[74:75] op_sel_hi:[1,0]
	v_pk_mul_f32 v[2:3], v[2:3], s[74:75] op_sel_hi:[1,0]
	v_pk_mul_f32 v[4:5], v[4:5], s[74:75] op_sel_hi:[1,0]
	v_exp_f32_e32 v6, v6
	s_waitcnt vmcnt(14)
	v_mov_b32_e32 v110, v222
	v_mov_b32_e32 v111, v223
	v_mov_b32_e32 v112, v224
	v_mov_b32_e32 v113, v225
	global_load_dwordx4 v[222:225], v[242:243], off offset:256
	v_lshlrev_b32_e32 v114, 16, v110
	v_and_b32_e32 v115, 0xffff0000, v110
	v_lshlrev_b32_e32 v110, 16, v111
	v_and_b32_e32 v111, 0xffff0000, v111
	v_lshlrev_b32_e32 v116, 16, v112
	v_and_b32_e32 v117, 0xffff0000, v112
	v_lshlrev_b32_e32 v112, 16, v113
	v_and_b32_e32 v113, 0xffff0000, v113
	v_pk_mul_f32 v[106:107], v[106:107], v[110:111]
	v_pk_mul_f32 v[104:105], v[104:105], v[114:115]
	v_pk_mul_f32 v[110:111], v[102:103], v[112:113]
	v_pk_mul_f32 v[102:103], v[100:101], v[116:117]
	v_cvt_pk_bf16_f32 v100, v104, v105
	v_cvt_pk_bf16_f32 v101, v106, v107
	v_cvt_pk_bf16_f32 v102, v102, v103
	v_cvt_pk_bf16_f32 v103, v110, v111
	global_store_dwordx4 v[108:109], v[100:103], off offset:256
	v_exp_f32_e32 v7, v7
	v_exp_f32_e32 v8, v8
	v_add_co_u32_e32 v100, vcc, s93, v162
	v_exp_f32_e32 v9, v9
	s_nop 0
	v_addc_co_u32_e32 v101, vcc, 0, v163, vcc
	v_exp_f32_e32 v2, v2
	v_exp_f32_e32 v3, v3
	v_exp_f32_e32 v4, v4
	v_exp_f32_e32 v5, v5
	v_pk_add_f32 v[6:7], v[6:7], 1.0 op_sel_hi:[1,0]
	v_pk_add_f32 v[8:9], v[8:9], 1.0 op_sel_hi:[1,0]
	v_pk_add_f32 v[2:3], v[2:3], 1.0 op_sel_hi:[1,0]
	v_pk_add_f32 v[4:5], v[4:5], 1.0 op_sel_hi:[1,0]
	v_rcp_f32_e32 v6, v6
	v_rcp_f32_e32 v7, v7
	v_rcp_f32_e32 v8, v8
	v_rcp_f32_e32 v9, v9
	v_rcp_f32_e32 v2, v2
	v_rcp_f32_e32 v3, v3
	v_rcp_f32_e32 v4, v4
	v_rcp_f32_e32 v5, v5
	s_waitcnt vmcnt(15)
; #define GAS __attribute__((address_space(1)))
; __device__ __forceinline__ u32x4 pack8(f32x4 v0, f32x4 v1) { u32x4 w; w.x = cvt_pk_bf16(v0[0], v0[1]); w.y = cvt_pk_bf16(v0[2], v0[3]); w.z = cvt_pk_bf16(v1[0], v1[1]); w.w = cvt_pk_bf16(v1[2], v1[3]); return w; }
; __device__ __forceinline__ void unpack8(u32x4 w, f32x4& v0, f32x4& v1) { v0 = (f32x4){bflo(w.x), bfhi(w.x), bflo(w.y), bfhi(w.y)}; v1 = (f32x4){bflo(w.z), bfhi(w.z), bflo(w.w), bfhi(w.w)}; }
; #define GAS __attribute__((address_space(1)))
;     __device__ __forceinline__ void operator()(const f32x4 (&acc)[2][2][4][2], const Unit& u, int wr, int wc, int fr, int fq) const {
;     ...
;         const bf16_t* const zb = Z + (size_t)row0 * 1024 + col0; bf16_t* const sob = SO + (size_t)row0 * 1024 + col0;
; #pragma unroll
;         for (int ai = 0; ai < 2; ++ai)
; #pragma unroll
;             for (int m = 0; m < 4; ++m) { const size_t off = (size_t)(ai * HALF + m * 16) * 1024;
; #pragma unroll
;                 for (int bj = 0; bj < 2; ++bj) { f32x4 z0, z1; unpack8(*(const GAS u32x4*)(zb + off + bj * HALF), z0, z1);
;                     const f32x4 v0 = z0 * sigmoid4(acc[ai][bj][m][0] + bv[bj][0]), v1 = z1 * sigmoid4(acc[ai][bj][m][1] + bv[bj][1]);
;                     *(GAS u32x4*)(sob + off + bj * HALF) = pack8(v0, v1); } }
	v_mov_b32_e32 v102, v226
	v_mov_b32_e32 v103, v227
	v_mov_b32_e32 v104, v228
	v_mov_b32_e32 v105, v229
	v_lshlrev_b32_e32 v106, 16, v102
	v_and_b32_e32 v107, 0xffff0000, v102
	v_lshlrev_b32_e32 v108, 16, v104
	v_and_b32_e32 v109, 0xffff0000, v104
	v_lshlrev_b32_e32 v102, 16, v103
	v_and_b32_e32 v103, 0xffff0000, v103
	v_lshlrev_b32_e32 v104, 16, v105
	v_and_b32_e32 v105, 0xffff0000, v105
	v_pk_mul_f32 v[94:95], v[94:95], v[106:107]
	v_pk_mul_f32 v[90:91], v[90:91], v[108:109]
	v_pk_mul_f32 v[96:97], v[96:97], v[102:103]
	v_pk_mul_f32 v[102:103], v[92:93], v[104:105]
	v_cvt_pk_bf16_f32 v92, v94, v95
	v_cvt_pk_bf16_f32 v94, v90, v91
	v_add_co_u32_e32 v90, vcc, s93, v160
	v_cvt_pk_bf16_f32 v93, v96, v97
	v_cvt_pk_bf16_f32 v95, v102, v103
	v_addc_co_u32_e32 v91, vcc, 0, v161, vcc
	global_store_dwordx4 v[90:91], v[92:95], off
	s_waitcnt vmcnt(15)
	v_mov_b32_e32 v92, v230
	v_mov_b32_e32 v93, v231
	v_mov_b32_e32 v94, v232
	v_mov_b32_e32 v95, v233
	v_lshlrev_b32_e32 v96, 16, v92
	v_and_b32_e32 v97, 0xffff0000, v92
	v_lshlrev_b32_e32 v92, 16, v93
	v_and_b32_e32 v93, 0xffff0000, v93
	v_lshlrev_b32_e32 v100, 16, v94
	v_and_b32_e32 v101, 0xffff0000, v94
	v_lshlrev_b32_e32 v94, 16, v95
	v_and_b32_e32 v95, 0xffff0000, v95
	v_pk_mul_f32 v[88:89], v[88:89], v[92:93]
	v_pk_mul_f32 v[86:87], v[86:87], v[96:97]
	v_pk_mul_f32 v[92:93], v[84:85], v[94:95]
	v_pk_mul_f32 v[84:85], v[82:83], v[100:101]
	v_cvt_pk_bf16_f32 v82, v86, v87
	v_cvt_pk_bf16_f32 v83, v88, v89
	v_cvt_pk_bf16_f32 v84, v84, v85
	v_cvt_pk_bf16_f32 v85, v92, v93
	global_store_dwordx4 v[90:91], v[82:85], off offset:256
	s_nop 1
	v_add_co_u32_e32 v82, vcc, s49, v162
	s_nop 1
	v_addc_co_u32_e32 v83, vcc, 0, v163, vcc
	s_waitcnt vmcnt(15)
	v_mov_b32_e32 v84, v234
	v_mov_b32_e32 v85, v235
	v_mov_b32_e32 v86, v236
	v_mov_b32_e32 v87, v237
	v_lshlrev_b32_e32 v88, 16, v84
	v_and_b32_e32 v89, 0xffff0000, v84
	v_lshlrev_b32_e32 v90, 16, v86
	v_and_b32_e32 v91, 0xffff0000, v86
	v_lshlrev_b32_e32 v84, 16, v85
	v_and_b32_e32 v85, 0xffff0000, v85
	v_lshlrev_b32_e32 v86, 16, v87
	v_and_b32_e32 v87, 0xffff0000, v87
	v_pk_mul_f32 v[78:79], v[78:79], v[88:89]
	v_pk_mul_f32 v[74:75], v[74:75], v[90:91]
	v_pk_mul_f32 v[80:81], v[80:81], v[84:85]
	v_pk_mul_f32 v[84:85], v[76:77], v[86:87]
	v_cvt_pk_bf16_f32 v76, v78, v79
	v_cvt_pk_bf16_f32 v78, v74, v75
	v_add_co_u32_e32 v74, vcc, s49, v160
	v_cvt_pk_bf16_f32 v77, v80, v81
	v_cvt_pk_bf16_f32 v79, v84, v85
	v_addc_co_u32_e32 v75, vcc, 0, v161, vcc
	global_store_dwordx4 v[74:75], v[76:79], off
	s_waitcnt vmcnt(15)
	v_mov_b32_e32 v76, v238
	v_mov_b32_e32 v77, v239
	v_mov_b32_e32 v78, v240
	v_mov_b32_e32 v79, v241
	v_lshlrev_b32_e32 v80, 16, v76
	v_and_b32_e32 v81, 0xffff0000, v76
	v_lshlrev_b32_e32 v76, 16, v77
	v_and_b32_e32 v77, 0xffff0000, v77
	v_lshlrev_b32_e32 v82, 16, v78
	v_and_b32_e32 v83, 0xffff0000, v78
	v_lshlrev_b32_e32 v78, 16, v79
	v_and_b32_e32 v79, 0xffff0000, v79
	v_pk_mul_f32 v[72:73], v[72:73], v[76:77]
	v_pk_mul_f32 v[70:71], v[70:71], v[80:81]
	v_pk_mul_f32 v[76:77], v[68:69], v[78:79]
	v_pk_mul_f32 v[68:69], v[66:67], v[82:83]
	v_cvt_pk_bf16_f32 v66, v70, v71
	v_cvt_pk_bf16_f32 v67, v72, v73
	v_cvt_pk_bf16_f32 v68, v68, v69
	v_cvt_pk_bf16_f32 v69, v76, v77
	global_store_dwordx4 v[74:75], v[66:69], off offset:256
	s_nop 1
	v_add_co_u32_e32 v66, vcc, s50, v162
	s_nop 1
	v_addc_co_u32_e32 v67, vcc, 0, v163, vcc
	s_waitcnt vmcnt(15)
	v_mov_b32_e32 v68, v184
	v_mov_b32_e32 v69, v185
	v_mov_b32_e32 v70, v186
	v_mov_b32_e32 v71, v187
	v_lshlrev_b32_e32 v72, 16, v68
	v_and_b32_e32 v73, 0xffff0000, v68
	v_lshlrev_b32_e32 v74, 16, v70
	v_and_b32_e32 v75, 0xffff0000, v70
	v_lshlrev_b32_e32 v68, 16, v69
	v_and_b32_e32 v69, 0xffff0000, v69
	v_lshlrev_b32_e32 v70, 16, v71
	v_and_b32_e32 v71, 0xffff0000, v71
	v_pk_mul_f32 v[62:63], v[62:63], v[72:73]
	v_pk_mul_f32 v[58:59], v[58:59], v[74:75]
	v_pk_mul_f32 v[64:65], v[64:65], v[68:69]
	v_pk_mul_f32 v[68:69], v[60:61], v[70:71]
	v_cvt_pk_bf16_f32 v60, v62, v63
	v_cvt_pk_bf16_f32 v62, v58, v59
	v_add_co_u32_e32 v58, vcc, s50, v160
	v_cvt_pk_bf16_f32 v61, v64, v65
	v_cvt_pk_bf16_f32 v63, v68, v69
	v_addc_co_u32_e32 v59, vcc, 0, v161, vcc
	global_store_dwordx4 v[58:59], v[60:63], off
	s_waitcnt vmcnt(15)
; #define GAS __attribute__((address_space(1)))
; __device__ __forceinline__ u32x4 pack8(f32x4 v0, f32x4 v1) { u32x4 w; w.x = cvt_pk_bf16(v0[0], v0[1]); w.y = cvt_pk_bf16(v0[2], v0[3]); w.z = cvt_pk_bf16(v1[0], v1[1]); w.w = cvt_pk_bf16(v1[2], v1[3]); return w; }
; __device__ __forceinline__ void unpack8(u32x4 w, f32x4& v0, f32x4& v1) { v0 = (f32x4){bflo(w.x), bfhi(w.x), bflo(w.y), bfhi(w.y)}; v1 = (f32x4){bflo(w.z), bfhi(w.z), bflo(w.w), bfhi(w.w)}; }
; #define GAS __attribute__((address_space(1)))
;     __device__ __forceinline__ void operator()(const f32x4 (&acc)[2][2][4][2], const Unit& u, int wr, int wc, int fr, int fq) const {
;     ...
;         const bf16_t* const zb = Z + (size_t)row0 * 1024 + col0; bf16_t* const sob = SO + (size_t)row0 * 1024 + col0;
; #pragma unroll
;         for (int ai = 0; ai < 2; ++ai)
; #pragma unroll
;             for (int m = 0; m < 4; ++m) { const size_t off = (size_t)(ai * HALF + m * 16) * 1024;
; #pragma unroll
;                 for (int bj = 0; bj < 2; ++bj) { f32x4 z0, z1; unpack8(*(const GAS u32x4*)(zb + off + bj * HALF), z0, z1);
;                     const f32x4 v0 = z0 * sigmoid4(acc[ai][bj][m][0] + bv[bj][0]), v1 = z1 * sigmoid4(acc[ai][bj][m][1] + bv[bj][1]);
;                     *(GAS u32x4*)(sob + off + bj * HALF) = pack8(v0, v1); } }
	v_mov_b32_e32 v60, v188
	v_mov_b32_e32 v61, v189
	v_mov_b32_e32 v62, v190
	v_mov_b32_e32 v63, v191
	v_lshlrev_b32_e32 v64, 16, v60
	v_and_b32_e32 v65, 0xffff0000, v60
	v_lshlrev_b32_e32 v60, 16, v61
	v_and_b32_e32 v61, 0xffff0000, v61
	v_lshlrev_b32_e32 v66, 16, v62
	v_and_b32_e32 v67, 0xffff0000, v62
	v_lshlrev_b32_e32 v62, 16, v63
	v_and_b32_e32 v63, 0xffff0000, v63
	v_pk_mul_f32 v[56:57], v[56:57], v[60:61]
	v_pk_mul_f32 v[54:55], v[54:55], v[64:65]
	v_pk_mul_f32 v[60:61], v[52:53], v[62:63]
	v_pk_mul_f32 v[52:53], v[50:51], v[66:67]
	v_cvt_pk_bf16_f32 v50, v54, v55
	v_cvt_pk_bf16_f32 v51, v56, v57
	v_cvt_pk_bf16_f32 v52, v52, v53
	v_cvt_pk_bf16_f32 v53, v60, v61
	global_store_dwordx4 v[58:59], v[50:53], off offset:256
	s_nop 1
	v_add_co_u32_e32 v50, vcc, s51, v162
	s_nop 1
	v_addc_co_u32_e32 v51, vcc, 0, v163, vcc
	s_waitcnt vmcnt(15)
	v_mov_b32_e32 v52, v192
	v_mov_b32_e32 v53, v193
	v_mov_b32_e32 v54, v194
	v_mov_b32_e32 v55, v195
	v_lshlrev_b32_e32 v56, 16, v52
	v_and_b32_e32 v57, 0xffff0000, v52
	v_lshlrev_b32_e32 v58, 16, v54
	v_and_b32_e32 v59, 0xffff0000, v54
	v_lshlrev_b32_e32 v52, 16, v53
	v_and_b32_e32 v53, 0xffff0000, v53
	v_lshlrev_b32_e32 v54, 16, v55
	v_and_b32_e32 v55, 0xffff0000, v55
	v_pk_mul_f32 v[46:47], v[46:47], v[56:57]
	v_pk_mul_f32 v[42:43], v[42:43], v[58:59]
	v_pk_mul_f32 v[48:49], v[48:49], v[52:53]
	v_pk_mul_f32 v[52:53], v[44:45], v[54:55]
	v_cvt_pk_bf16_f32 v44, v46, v47
	v_cvt_pk_bf16_f32 v46, v42, v43
	v_add_co_u32_e32 v42, vcc, s51, v160
	v_cvt_pk_bf16_f32 v45, v48, v49
	v_cvt_pk_bf16_f32 v47, v52, v53
	v_addc_co_u32_e32 v43, vcc, 0, v161, vcc
	global_store_dwordx4 v[42:43], v[44:47], off
	s_waitcnt vmcnt(15)
	v_mov_b32_e32 v44, v196
	v_mov_b32_e32 v45, v197
	v_mov_b32_e32 v46, v198
	v_mov_b32_e32 v47, v199
	v_lshlrev_b32_e32 v48, 16, v44
	v_and_b32_e32 v49, 0xffff0000, v44
	v_lshlrev_b32_e32 v44, 16, v45
	v_and_b32_e32 v45, 0xffff0000, v45
	v_lshlrev_b32_e32 v50, 16, v46
	v_and_b32_e32 v51, 0xffff0000, v46
	v_lshlrev_b32_e32 v46, 16, v47
	v_and_b32_e32 v47, 0xffff0000, v47
	v_pk_mul_f32 v[32:33], v[32:33], v[44:45]
	v_pk_mul_f32 v[30:31], v[30:31], v[48:49]
	v_pk_mul_f32 v[44:45], v[28:29], v[46:47]
	v_pk_mul_f32 v[28:29], v[26:27], v[50:51]
	v_cvt_pk_bf16_f32 v26, v30, v31
	v_cvt_pk_bf16_f32 v27, v32, v33
	v_cvt_pk_bf16_f32 v28, v28, v29
	v_cvt_pk_bf16_f32 v29, v44, v45
	global_store_dwordx4 v[42:43], v[26:29], off offset:256
	s_nop 1
	v_add_co_u32_e32 v26, vcc, s66, v162
	s_nop 1
	v_addc_co_u32_e32 v27, vcc, 0, v163, vcc
	s_waitcnt vmcnt(15)
	v_mov_b32_e32 v28, v200
	v_mov_b32_e32 v29, v201
	v_mov_b32_e32 v30, v202
	v_mov_b32_e32 v31, v203
	v_lshlrev_b32_e32 v32, 16, v28
	v_and_b32_e32 v33, 0xffff0000, v28
	v_lshlrev_b32_e32 v28, 16, v29
	v_and_b32_e32 v29, 0xffff0000, v29
	v_lshlrev_b32_e32 v42, 16, v30
	v_and_b32_e32 v43, 0xffff0000, v30
	v_lshlrev_b32_e32 v30, 16, v31
	v_and_b32_e32 v31, 0xffff0000, v31
	v_pk_mul_f32 v[18:19], v[18:19], v[32:33]
	v_pk_mul_f32 v[20:21], v[20:21], v[28:29]
	v_pk_mul_f32 v[28:29], v[12:13], v[30:31]
	v_pk_mul_f32 v[12:13], v[10:11], v[42:43]
	v_cvt_pk_bf16_f32 v10, v18, v19
	v_add_co_u32_e32 v18, vcc, s66, v160
	v_cvt_pk_bf16_f32 v11, v20, v21
	v_cvt_pk_bf16_f32 v12, v12, v13
	v_cvt_pk_bf16_f32 v13, v28, v29
	v_addc_co_u32_e32 v19, vcc, 0, v161, vcc
	global_store_dwordx4 v[18:19], v[10:13], off
	s_andn2_b64 vcc, exec, s[18:19]
	s_waitcnt vmcnt(15)
	v_mov_b32_e32 v10, v222
	v_mov_b32_e32 v11, v223
	v_mov_b32_e32 v12, v224
	v_mov_b32_e32 v13, v225
	v_lshlrev_b32_e32 v20, 16, v10
	v_and_b32_e32 v21, 0xffff0000, v10
	v_lshlrev_b32_e32 v10, 16, v11
	v_and_b32_e32 v11, 0xffff0000, v11
	v_lshlrev_b32_e32 v26, 16, v12
	v_and_b32_e32 v27, 0xffff0000, v12
	v_lshlrev_b32_e32 v12, 16, v13
	v_and_b32_e32 v13, 0xffff0000, v13
	v_pk_mul_f32 v[8:9], v[8:9], v[10:11]
	v_pk_mul_f32 v[6:7], v[6:7], v[20:21]
	v_pk_mul_f32 v[10:11], v[4:5], v[12:13]
	v_pk_mul_f32 v[4:5], v[2:3], v[26:27]
	v_cvt_pk_bf16_f32 v2, v6, v7
	v_cvt_pk_bf16_f32 v3, v8, v9
	v_cvt_pk_bf16_f32 v4, v4, v5
	v_cvt_pk_bf16_f32 v5, v10, v11
	global_store_dwordx4 v[18:19], v[2:5], off offset:256
	s_cbranch_vccnz .LBB0_923
	s_andn2_b64 vcc, exec, s[6:7]
	s_cbranch_vccnz .LBB0_922
	s_barrier
	s_branch .LBB0_922
